# gating: dropped the per-unit vmcnt(0) at the unit top (it only drained the previous unit's MIX stores); preamble waits once
# speedup vs baseline: 1.0056x; 1.0056x over previous
; __device__ __forceinline__ int tid_fresh() { int t = threadIdx.x; asm volatile("" : "+v"(t)); return t; }
; __device__ __forceinline__ void gate_phase(int bx, int G, bool skip_ctx, const bf16* __restrict__ VG, const bf16* __restrict__ U, const float* __restrict__ stats, ...
;     const int tid = tid_fresh(), wid = tid >> 6, lane = tid & 63, r32 = lane & 31, hi = lane >> 5;
;     bf16* T = (bf16*)lds;
;     const int q = tid >> 2, dc = (tid & 3) * 16;
;     const int db = wid & 1, pb = wid >> 1, p = pb * 32 + r32;
;     const int NU = (M / 128) * 8;
;     auto unit_ok = [&](int u) { return u < NU && !(skip_ctx && ((u >> 3) % 34) < 2); };
;     auto next_unit = [&](int u) { u += G; while (u < NU && !unit_ok(u)) u += G; return u; };
;     int u = bx; if (!unit_ok(u)) u = next_unit(u);
;     GateRegs R;
;     ...
;     if (u < NU) GATE_LOAD(u);
;     ...
;             const float* gp = gsg + h * 64 + dc; const float* bp = bsg + h * 64 + dc;
;     ...
;         const float bias = bsl[h * 128 + p];
.LBB0_39:
	s_cmpk_gt_i32 s3, 0x87f
	s_cbranch_scc1 .LBB0_51
	s_lshl_b32 s22, s12, 9
	s_ashr_i32 s23, s22, 31
	s_lshl_b64 s[26:27], s[22:23], 2
	s_waitcnt lgkmcnt(0)
	s_add_u32 s22, s8, s26
	s_addc_u32 s23, s9, s27
	s_add_u32 s26, s10, s26
	s_addc_u32 s27, s11, s27
	s_ashr_i32 s13, s12, 31
	s_lshl_b64 s[8:9], s[12:13], 18
	s_add_u32 s8, s28, s8
	s_addc_u32 s9, s29, s9
	s_add_u32 s38, s8, 0x5800000
	s_addc_u32 s39, s9, 0
	s_lshl_b32 s8, s12, 10
	s_ashr_i32 s9, s8, 31
	s_lshl_b64 s[8:9], s[8:9], 2
	s_add_u32 s6, s6, s8
	s_addc_u32 s7, s7, s9
	v_ashrrev_i32_e32 v100, 2, v4
	s_movk_i32 s8, 0xffe0
	v_bfi_b32 v102, s8, v100, v4
	s_add_u32 s8, s28, 0x11efa000
	s_addc_u32 s9, s29, 0
	s_add_u32 s10, s28, 0x140fa000
	s_addc_u32 s11, s29, 0
	s_ashr_i32 s46, s3, 3
	s_ashr_i32 s47, s46, 31
	v_lshlrev_b32_e32 v0, 4, v4
	s_lshl_b64 s[46:47], s[46:47], 7
	v_ashrrev_i32_e32 v101, 31, v100
	v_and_b32_e32 v6, 48, v0
	v_lshl_add_u64 v[0:1], s[46:47], 0, v[100:101]
	s_and_b32 s13, s3, 7
	v_lshlrev_b64 v[2:3], 6, v[0:1]
	v_lshlrev_b64 v[0:1], 10, v[0:1]
	v_lshl_add_u64 v[0:1], s[10:11], 0, v[0:1]
	s_lshl_b32 s72, s13, 7
	v_lshl_add_u64 v[0:1], v[0:1], 0, s[72:73]
	v_lshlrev_b32_e32 v160, 1, v6
	v_lshl_add_u64 v[2:3], s[40:41], 0, v[2:3]
	v_lshl_add_u64 v[0:1], v[0:1], 0, v[160:161]
	v_ashrrev_i32_e32 v103, 31, v102
	global_load_dwordx4 v[16:19], v[2:3], off offset:48
	global_load_dwordx4 v[20:23], v[2:3], off offset:32
	global_load_dwordx4 v[24:27], v[2:3], off offset:16
	global_load_dwordx4 v[28:31], v[2:3], off
	global_load_dwordx4 v[32:35], v[0:1], off offset:16 nt
	global_load_dwordx4 v[36:39], v[0:1], off nt
	v_lshl_add_u64 v[0:1], s[46:47], 0, v[102:103]
	v_lshlrev_b64 v[0:1], 10, v[0:1]
	v_lshrrev_b32_e32 v2, 1, v4
	v_lshl_add_u64 v[0:1], s[8:9], 0, v[0:1]
	v_and_b32_e32 v8, 32, v2
	v_bfe_u32 v5, v4, 5, 1
	v_lshl_add_u64 v[0:1], v[0:1], 0, s[72:73]
	v_lshlrev_b32_e32 v160, 1, v8
	v_lshl_add_u64 v[0:1], v[0:1], 0, v[160:161]
	v_lshlrev_b32_e32 v160, 3, v5
	v_lshl_add_u64 v[0:1], v[0:1], 0, v[160:161]
	global_load_dwordx2 v[124:125], v[0:1], off nt
	global_load_dwordx2 v[122:123], v[0:1], off offset:16 nt
	global_load_dwordx2 v[120:121], v[0:1], off offset:32 nt
	global_load_dwordx2 v[106:107], v[0:1], off offset:48 nt
	v_lshl_add_u64 v[0:1], s[72:73], 0, v[102:103]
	v_lshlrev_b64 v[0:1], 8, v[0:1]
	v_lshl_add_u64 v[0:1], s[38:39], 0, v[0:1]
	v_lshlrev_b32_e32 v160, 4, v5
	v_lshl_add_u64 v[10:11], v[0:1], 0, v[160:161]
	global_load_dwordx4 v[0:3], v[10:11], off
	global_load_dwordx4 v[60:63], v[10:11], off offset:32
	global_load_dwordx4 v[64:67], v[10:11], off offset:64
	global_load_dwordx4 v[52:55], v[10:11], off offset:96
	global_load_dwordx4 v[56:59], v[10:11], off offset:128
	global_load_dwordx4 v[48:51], v[10:11], off offset:160
	global_load_dwordx4 v[44:47], v[10:11], off offset:192
	global_load_dwordx4 v[40:43], v[10:11], off offset:224
	v_lshlrev_b32_e32 v10, 2, v5
	v_lshlrev_b32_e32 v12, 2, v6
	v_mov_b32_e32 v13, v161
	v_and_or_b32 v4, v4, 31, v8
	s_movk_i32 s13, 0x110
	v_mul_u32_u24_e32 v9, 0x88, v6
	v_lshl_add_u64 v[104:105], s[22:23], 0, v[12:13]
	v_lshl_add_u64 v[108:109], s[26:27], 0, v[12:13]
	v_lshlrev_b32_e32 v5, 1, v100
	v_mad_u32_u24 v7, v4, s13, 0
	v_or_b32_e32 v4, v10, v8
	v_lshlrev_b64 v[12:13], 11, v[102:103]
	v_lshlrev_b32_e32 v9, 1, v9
	v_lshl_add_u64 v[110:111], s[38:39], 0, v[160:161]
	v_lshl_add_u64 v[112:113], s[16:17], 0, v[12:13]
	v_add3_u32 v134, 0, v5, v9
	v_add3_u32 v135, 0, v9, v5
	v_lshlrev_b32_e32 v114, 1, v6
	v_lshlrev_b32_e32 v116, 1, v8
	v_lshlrev_b32_e32 v118, 1, v10
	v_add_u32_e32 v136, v7, v160
	v_lshlrev_b32_e32 v160, 1, v4
	s_and_b32 s37, s3, 7
	s_lshl_b32 s38, s37, 8
	s_mov_b32 s39, 0
	v_lshl_add_u64 v[252:253], v[104:105], 0, s[38:39]
	global_load_dwordx4 v[218:221], v[252:253], off
	global_load_dwordx4 v[222:225], v[252:253], off offset:16
	global_load_dwordx4 v[226:229], v[252:253], off offset:32
	global_load_dwordx4 v[230:233], v[252:253], off offset:48
	v_lshl_add_u64 v[252:253], v[108:109], 0, s[38:39]
	global_load_dwordx4 v[234:237], v[252:253], off
	global_load_dwordx4 v[238:241], v[252:253], off offset:16
	global_load_dwordx4 v[242:245], v[252:253], off offset:32
	global_load_dwordx4 v[246:249], v[252:253], off offset:48
	v_lshl_add_u32 v252, s37, 7, v102
	v_ashrrev_i32_e32 v253, 31, v252
	v_lshl_add_u64 v[252:253], v[252:253], 2, s[6:7]
	global_load_dword v137, v[252:253], off
	s_waitcnt vmcnt(0)
	s_branch .LBB0_45

; __device__ __forceinline__ unsigned f2bf(float f) { unsigned u = __builtin_bit_cast(unsigned, f); return (u + 0x7fffu + ((u >> 16) & 1u)) >> 16; }
; __device__ __forceinline__ float bflo(unsigned w) { return __uint_as_float(w << 16); }
; __device__ __forceinline__ float bfhi(unsigned w) { return __uint_as_float(w & 0xffff0000u); }
; __device__ __forceinline__ void gate_phase(int bx, int G, bool skip_ctx, const bf16* __restrict__ VG, const bf16* __restrict__ U, const float* __restrict__ stats, ...
;     ...
;         const int chunk = u >> 3, h = u & 7;
;         {
;             const float s1 = (R.sa[0] + R.sa[2]) + (R.sb[0] + R.sb[2]) + (R.sc[0] + R.sc[2]) + (R.sd[0] + R.sd[2]);
;             const float s2 = (R.sa[1] + R.sa[3]) + (R.sb[1] + R.sb[3]) + (R.sc[1] + R.sc[3]) + (R.sd[1] + R.sd[3]);
;             const float mean = s1 * (1.0f / 512.0f);
;             const float var = fmaxf(s2 * (1.0f / 512.0f) - mean * mean, 0.f);
;             const float rstd = __builtin_amdgcn_rsqf(var + EPS);
;             const float* gp = gsg + h * 64 + dc; const float* bp = bsg + h * 64 + dc;
; #pragma unroll
;             for (int i = 0; i < 8; ++i) {
;                 const unsigned w = i < 4 ? R.v0[i] : R.v1[i - 4];
;                 const float x0 = (bflo(w) - mean) * rstd * gp[2 * i] + bp[2 * i], x1 = (bfhi(w) - mean) * rstd * gp[2 * i + 1] + bp[2 * i + 1];
;                 T[(dc + 2 * i) * GT_PITCH + q] = (bf16)f2bf(x0); T[(dc + 2 * i + 1) * GT_PITCH + q] = (bf16)f2bf(x1);
;             }
.LBB0_45:
	s_and_b32 s22, s3, 7
	s_lshl_b32 s72, s22, 8
	s_waitcnt vmcnt(23)
	v_add_f32_e32 v82, v28, v30
	v_add_f32_e32 v83, v24, v26
	v_add_f32_e32 v88, v29, v31
	v_add_f32_e32 v89, v25, v27
	v_add_f32_e32 v86, v20, v22
	v_add_f32_e32 v90, v21, v23
	v_add_f32_e32 v82, v83, v82
	v_add_f32_e32 v83, v89, v88
	v_add_f32_e32 v87, v16, v18
	v_add_f32_e32 v91, v17, v19
	v_add_f32_e32 v82, v86, v82
	v_add_f32_e32 v83, v90, v83
	v_add_f32_e32 v90, v87, v82
	v_add_f32_e32 v91, v91, v83
	s_nop 0
	v_mul_f32_e32 v115, 0x3b000000, v90
	s_lshl_b32 s19, s22, 6
	v_mul_f32_e32 v115, v115, v115
	s_mov_b32 s22, 0x3b000000
	v_fma_f32 v91, v91, s22, -v115
	v_max_f32_e32 v91, 0, v91
	v_add_f32_e32 v91, 0x358637bd, v91
	v_rsq_f32_e32 v91, v91
	s_waitcnt vmcnt(21)
	v_lshlrev_b32_e32 v92, 16, v36
	v_lshlrev_b32_e32 v94, 16, v37
	v_lshlrev_b32_e32 v96, 16, v38
	v_and_b32_e32 v93, 0xffff0000, v36
	v_and_b32_e32 v95, 0xffff0000, v37
	v_and_b32_e32 v97, 0xffff0000, v38
	v_fmac_f32_e32 v92, 0xbb000000, v90
	v_fmac_f32_e32 v94, 0xbb000000, v90
	v_fmac_f32_e32 v96, 0xbb000000, v90
	v_lshlrev_b32_e32 v98, 16, v39
	v_fmac_f32_e32 v93, 0xbb000000, v90
	v_fmac_f32_e32 v95, 0xbb000000, v90
	v_fmac_f32_e32 v97, 0xbb000000, v90
	v_mul_f32_e32 v88, v92, v91
	v_mul_f32_e32 v92, v94, v91
	v_mul_f32_e32 v94, v96, v91
	v_fmac_f32_e32 v98, 0xbb000000, v90
	v_mul_f32_e32 v89, v93, v91
	v_mul_f32_e32 v93, v95, v91
	v_mul_f32_e32 v95, v97, v91
	v_and_b32_e32 v99, 0xffff0000, v39
	v_mul_f32_e32 v96, v98, v91
	v_fmac_f32_e32 v99, 0xbb000000, v90
	v_mul_f32_e32 v97, v99, v91
	s_mov_b32 s13, s3
	v_fma_f32 v68, v88, v218, v234
	v_fma_f32 v69, v89, v219, v235
	v_fma_f32 v12, v94, v222, v238
	v_fma_f32 v70, v92, v220, v236
	v_fma_f32 v71, v93, v221, v237
	v_fma_f32 v13, v95, v223, v239
	v_bfe_u32 v72, v68, 16, 1
	v_bfe_u32 v76, v12, 16, 1
	v_fma_f32 v14, v96, v224, v240
	v_bfe_u32 v73, v69, 16, 1
	v_bfe_u32 v74, v70, 16, 1
	v_bfe_u32 v75, v71, 16, 1
	v_bfe_u32 v77, v13, 16, 1
	v_add3_u32 v68, v68, v72, s56
	v_add3_u32 v12, v12, v76, s56
	v_add3_u32 v69, v69, v73, s56
	v_add3_u32 v70, v70, v74, s56
	v_add3_u32 v71, v71, v75, s56
	v_add3_u32 v13, v13, v77, s56
	ds_write_b16_d16_hi v134, v68
	ds_write_b16_d16_hi v135, v69 offset:272
	ds_write_b16_d16_hi v134, v70 offset:544
	ds_write_b16_d16_hi v135, v71 offset:816
	ds_write_b16_d16_hi v134, v12 offset:1088
	ds_write_b16_d16_hi v135, v13 offset:1360
	v_bfe_u32 v12, v14, 16, 1
	v_fma_f32 v15, v97, v225, v241
	v_add3_u32 v12, v14, v12, s56
	ds_write_b16_d16_hi v134, v12 offset:1632
	v_bfe_u32 v12, v15, 16, 1
	v_add3_u32 v12, v15, v12, s56
	ds_write_b16_d16_hi v135, v12 offset:1904
	v_lshlrev_b32_e32 v12, 16, v32
	v_fmac_f32_e32 v12, 0xbb000000, v90
	v_mul_f32_e32 v12, v12, v91
	v_fma_f32 v4, v12, v226, v242
	v_and_b32_e32 v8, 0xffff0000, v32
	v_fmac_f32_e32 v8, 0xbb000000, v90
	v_mul_f32_e32 v8, v8, v91
	v_fma_f32 v5, v8, v227, v243
	v_bfe_u32 v8, v4, 16, 1
	v_add3_u32 v4, v4, v8, s56
	ds_write_b16_d16_hi v134, v4 offset:2176
	v_bfe_u32 v4, v5, 16, 1
	v_add3_u32 v4, v5, v4, s56
	ds_write_b16_d16_hi v135, v4 offset:2448
	v_lshlrev_b32_e32 v4, 16, v33
	v_fmac_f32_e32 v4, 0xbb000000, v90
	v_and_b32_e32 v5, 0xffff0000, v33
	v_mul_f32_e32 v4, v4, v91
	v_fmac_f32_e32 v5, 0xbb000000, v90
	v_fma_f32 v4, v4, v228, v244
	v_mul_f32_e32 v5, v5, v91
	v_fma_f32 v7, v5, v229, v245
	v_bfe_u32 v5, v4, 16, 1
	v_add3_u32 v4, v4, v5, s56
	ds_write_b16_d16_hi v134, v4 offset:2720
	v_bfe_u32 v4, v7, 16, 1
	v_add3_u32 v4, v7, v4, s56
	ds_write_b16_d16_hi v135, v4 offset:2992
	v_lshlrev_b32_e32 v4, 16, v34
	v_fmac_f32_e32 v4, 0xbb000000, v90
	v_mul_f32_e32 v4, v4, v91
	v_and_b32_e32 v5, 0xffff0000, v34
	v_fma_f32 v4, v4, v230, v246
	v_fmac_f32_e32 v5, 0xbb000000, v90
	v_mul_f32_e32 v5, v5, v91
	v_bfe_u32 v6, v4, 16, 1
	v_fma_f32 v5, v5, v231, v247
	v_add3_u32 v4, v4, v6, s56
	ds_write_b16_d16_hi v134, v4 offset:3264
	v_bfe_u32 v4, v5, 16, 1
	v_add3_u32 v4, v5, v4, s56
	ds_write_b16_d16_hi v135, v4 offset:3536
	v_lshlrev_b32_e32 v4, 16, v35
	v_fmac_f32_e32 v4, 0xbb000000, v90
	v_and_b32_e32 v5, 0xffff0000, v35
	v_mul_f32_e32 v4, v4, v91
	v_fmac_f32_e32 v5, 0xbb000000, v90
	v_fma_f32 v4, v4, v232, v248
	v_mul_f32_e32 v5, v5, v91
	v_fma_f32 v87, v5, v233, v249
	v_bfe_u32 v5, v4, 16, 1
	v_add3_u32 v4, v4, v5, s56
	ds_write_b16_d16_hi v134, v4 offset:3808
	v_bfe_u32 v4, v87, 16, 1
	v_add3_u32 v4, v87, v4, s56
	ds_write_b16_d16_hi v135, v4 offset:4080
	s_branch .LBB0_47
